# HL Toeplitz loop: activation fragments kept in registers and shifted one lane per block-shift (DPP row_shr), only q==0 lanes read LDS; out-of-range rows read a zero row
# speedup vs baseline: 1.0041x; 1.0041x over previous
.LBB0_765:
	s_or_b64 exec, exec, s[2:3]
	v_mov_b32_e32 v10, 0
	s_xor_b64 s[2:3], s[4:5], -1
	s_mov_b64 s[16:17], 0
	v_mov_b32_e32 v38, v59
	v_mov_b32_e32 v39, v58
	v_mov_b32_e32 v40, v57
	v_mov_b32_e32 v41, v56
	v_mov_b32_e32 v11, v10
	v_mov_b32_e32 v12, v10
	v_mov_b32_e32 v13, v10
	v_mov_b32_e32 v6, v10
	v_mov_b32_e32 v7, v10
	v_mov_b32_e32 v8, v10
	v_mov_b32_e32 v9, v10
	v_and_b32_e32 v62, 7, v130
	v_mov_b32_e32 v64, 0
	v_mov_b32_e32 v65, 0
	v_mov_b32_e32 v66, 0
	v_mov_b32_e32 v67, 0
	v_lshlrev_b32_e32 v62, 4, v62
	v_add_u32_e32 v62, 142592, v62
	ds_write_b128 v62, v[64:67]
	s_waitcnt lgkmcnt(0)
	s_barrier
.LBB0_766:
	v_sub_u32_e32 v62, v44, v41
	v_and_b32_e32 v63, 15, v130
	v_readfirstlane_b32 s100, v62
	v_cmp_eq_u32_e32 vcc, 0, v63
	v_bfe_u32 v63, v130, 4, 2
	v_lshlrev_b32_e32 v63, 4, v63
	v_add_u32_e32 v63, 142592, v63
	v_cmp_gt_u32_e64 s[16:17], 32, v38
	v_add_u32_e32 v41, 1, v41
	v_add_u32_e32 v38, -1, v38
	ds_read_b128 v[80:83], v39
	ds_read_b128 v[84:87], v39 offset:64
	v_sub_u32_e32 v42, v1, v41
	ds_read_b128 v[88:91], v40
	ds_read_b128 v[92:95], v40 offset:64
	v_mad_u32_u24 v42, v42, s21, v18
	v_add_u32_e32 v39, 0xffffff80, v39
	v_add_u32_e32 v40, 0xffffff80, v40
	v_cndmask_b32_e64 v42, v63, v42, s[16:17]
	ds_read_b128 v[96:99], v42
	ds_read_b128 v[100:103], v42 offset:64
	s_sub_u32 s100, s100, 1
	s_cmp_eq_u32 s100, 0
	s_cbranch_scc1 .Lhl_tail_x
.Lhl_loop:
	v_cmp_gt_u32_e64 s[16:17], 32, v38
	v_add_u32_e32 v41, 1, v41
	v_add_u32_e32 v38, -1, v38
	ds_read_b128 v[104:107], v39
	ds_read_b128 v[108:111], v39 offset:64
	v_sub_u32_e32 v42, v1, v41
	ds_read_b128 v[112:115], v40
	ds_read_b128 v[116:119], v40 offset:64
	v_mad_u32_u24 v42, v42, s21, v18
	v_add_u32_e32 v39, 0xffffff80, v39
	v_add_u32_e32 v40, 0xffffff80, v40
	v_cndmask_b32_e64 v42, v63, v42, s[16:17]
	s_mov_b64 exec, vcc
	ds_read_b128 v[120:123], v42
	ds_read_b128 v[124:127], v42 offset:64
	s_mov_b64 exec, -1
	s_sub_u32 s100, s100, 1
	s_waitcnt lgkmcnt(6)
	v_mov_b32_dpp v120, v96 row_shr:1 row_mask:0xf bank_mask:0xf
	v_mov_b32_dpp v121, v97 row_shr:1 row_mask:0xf bank_mask:0xf
	v_mov_b32_dpp v122, v98 row_shr:1 row_mask:0xf bank_mask:0xf
	v_mov_b32_dpp v123, v99 row_shr:1 row_mask:0xf bank_mask:0xf
	v_mov_b32_dpp v124, v100 row_shr:1 row_mask:0xf bank_mask:0xf
	v_mov_b32_dpp v125, v101 row_shr:1 row_mask:0xf bank_mask:0xf
	v_mov_b32_dpp v126, v102 row_shr:1 row_mask:0xf bank_mask:0xf
	v_mov_b32_dpp v127, v103 row_shr:1 row_mask:0xf bank_mask:0xf
	v_mfma_f32_16x16x32_bf16 v[10:13], v[80:83], v[96:99], v[10:13]
	v_mfma_f32_16x16x32_bf16 v[6:9], v[88:91], v[96:99], v[6:9]
	v_mfma_f32_16x16x32_bf16 v[10:13], v[84:87], v[100:103], v[10:13]
	v_mfma_f32_16x16x32_bf16 v[6:9], v[92:95], v[100:103], v[6:9]
	s_cmp_eq_u32 s100, 0
	s_cbranch_scc1 .Lhl_tail_y
	v_cmp_gt_u32_e64 s[16:17], 32, v38
	v_add_u32_e32 v41, 1, v41
	v_add_u32_e32 v38, -1, v38
	ds_read_b128 v[80:83], v39
	ds_read_b128 v[84:87], v39 offset:64
	v_sub_u32_e32 v42, v1, v41
	ds_read_b128 v[88:91], v40
	ds_read_b128 v[92:95], v40 offset:64
	v_mad_u32_u24 v42, v42, s21, v18
	v_add_u32_e32 v39, 0xffffff80, v39
	v_add_u32_e32 v40, 0xffffff80, v40
	v_cndmask_b32_e64 v42, v63, v42, s[16:17]
	s_mov_b64 exec, vcc
	ds_read_b128 v[96:99], v42
	ds_read_b128 v[100:103], v42 offset:64
	s_mov_b64 exec, -1
	s_sub_u32 s100, s100, 1
	s_waitcnt lgkmcnt(6)
	v_mov_b32_dpp v96, v120 row_shr:1 row_mask:0xf bank_mask:0xf
	v_mov_b32_dpp v97, v121 row_shr:1 row_mask:0xf bank_mask:0xf
	v_mov_b32_dpp v98, v122 row_shr:1 row_mask:0xf bank_mask:0xf
	v_mov_b32_dpp v99, v123 row_shr:1 row_mask:0xf bank_mask:0xf
	v_mov_b32_dpp v100, v124 row_shr:1 row_mask:0xf bank_mask:0xf
	v_mov_b32_dpp v101, v125 row_shr:1 row_mask:0xf bank_mask:0xf
	v_mov_b32_dpp v102, v126 row_shr:1 row_mask:0xf bank_mask:0xf
	v_mov_b32_dpp v103, v127 row_shr:1 row_mask:0xf bank_mask:0xf
	v_mfma_f32_16x16x32_bf16 v[10:13], v[104:107], v[120:123], v[10:13]
	v_mfma_f32_16x16x32_bf16 v[6:9], v[112:115], v[120:123], v[6:9]
	v_mfma_f32_16x16x32_bf16 v[10:13], v[108:111], v[124:127], v[10:13]
	v_mfma_f32_16x16x32_bf16 v[6:9], v[116:119], v[124:127], v[6:9]
	s_cmp_eq_u32 s100, 0
	s_cbranch_scc0 .Lhl_loop
.Lhl_tail_x:
	s_waitcnt lgkmcnt(0)
	v_mfma_f32_16x16x32_bf16 v[10:13], v[80:83], v[96:99], v[10:13]
	v_mfma_f32_16x16x32_bf16 v[6:9], v[88:91], v[96:99], v[6:9]
	v_mfma_f32_16x16x32_bf16 v[10:13], v[84:87], v[100:103], v[10:13]
	v_mfma_f32_16x16x32_bf16 v[6:9], v[92:95], v[100:103], v[6:9]
	s_branch .Lhl_done
.Lhl_tail_y:
	s_waitcnt lgkmcnt(0)
	v_mfma_f32_16x16x32_bf16 v[10:13], v[104:107], v[120:123], v[10:13]
	v_mfma_f32_16x16x32_bf16 v[6:9], v[112:115], v[120:123], v[6:9]
	v_mfma_f32_16x16x32_bf16 v[10:13], v[108:111], v[124:127], v[10:13]
	v_mfma_f32_16x16x32_bf16 v[6:9], v[116:119], v[124:127], v[6:9]
